# v67 + P4: sample out-projection publish (store-ack wait + barrier + counter add) folded into the GEMM prologue's existing vmcnt(0), off the head of P4
# speedup vs baseline: 1.0043x; 1.0043x over previous
.LBB0_3568:
	s_cmpk_eq_i32 s56, 0x100
	s_cbranch_scc1 .Lpub_moved
	s_waitcnt vmcnt(0)
	s_cmp_lg_u32 s10, 0
	v_cmp_eq_u32_e32 vcc, 0, v4
	s_cselect_b64 s[0:1], -1, 0
	s_and_b64 s[4:5], vcc, s[0:1]
	s_waitcnt lgkmcnt(0)
	s_barrier
	s_and_saveexec_b64 s[0:1], s[4:5]
	s_cbranch_execz .LBB0_3571
	s_mov_b64 s[4:5], exec
	v_mbcnt_lo_u32_b32 v0, s4, 0
	v_mbcnt_hi_u32_b32 v0, s5, v0
	v_cmp_eq_u32_e32 vcc, 0, v0
	s_and_b64 s[6:7], exec, vcc
	s_mov_b64 exec, s[6:7]
	s_cbranch_execz .LBB0_3571
	s_bcnt1_i32_b64 s4, s[4:5]
	s_mul_i32 s4, s10, s4
	v_mov_b32_e32 v0, 0
	v_mov_b32_e32 v1, s4
	global_atomic_add v0, v1, s[2:3] offset:512

.Lpub_moved:
	v_readlane_b32 s2, v254, 0
	v_readlane_b32 s3, v254, 1
	s_cmpk_lg_i32 s56, 0x100
	s_cbranch_scc1 .LBB0_3638
	s_load_dwordx2 s[14:15], s[2:3], 0x80
	v_mov_b32_e32 v0, 0
	v_mov_b32_e32 v1, 0x4000
	v_readlane_b32 s0, v254, 3
	s_and_b64 vcc, exec, s[52:53]
	s_waitcnt lgkmcnt(0)
	global_load_dword v178, v0, s[14:15] sc1
	global_load_dword v179, v1, s[14:15] offset:512 sc1
	v_mbcnt_lo_u32_b32 v0, -1, 0
	v_mbcnt_hi_u32_b32 v0, -1, v0
	s_nop 0
	v_add_u32_e32 v183, s0, v0
	s_nop 0
	v_readfirstlane_b32 s38, v183
	s_cbranch_vccnz .LBB0_3638
	s_lshr_b32 s0, s97, 29
	s_add_i32 s16, s96, s0
	s_and_b32 s0, s16, -8
	s_sub_i32 s13, s96, s0
	s_cmp_gt_i32 s13, -1
	s_cbranch_scc0 .LBB0_3575
	s_lshl_b32 s12, s13, 5
	s_mov_b64 s[4:5], 0
	s_branch .LBB0_3576

.LBB0_3580:
	s_mov_b32 s0, 0x3f9837f0
	s_mov_b64 s[18:19], 0x80
	s_waitcnt vmcnt(0)
	s_barrier
	v_cmp_eq_u32_e32 vcc, 0x100, v183
	s_and_saveexec_b64 s[20:21], vcc
	s_cbranch_execz .Lpub_skip
	v_mov_b32_e32 v106, 0
	v_mov_b32_e32 v107, 1
	global_atomic_add v106, v107, s[14:15] offset:512
.Lpub_skip:
	s_or_b64 exec, exec, s[20:21]
	v_pk_mul_f32 v[106:107], v[86:87], s[0:1] op_sel_hi:[1,0]
	v_pk_mul_f32 v[86:87], v[66:67], s[0:1] op_sel_hi:[1,0]
	v_pk_mul_f32 v[66:67], v[50:51], s[0:1] op_sel_hi:[1,0]
	v_pk_mul_f32 v[50:51], v[6:7], s[0:1] op_sel_hi:[1,0]
	s_add_i32 m0, s17, 0x18000
	v_lshl_add_u64 v[6:7], v[102:103], 0, s[18:19]
	v_pk_mul_f32 v[104:105], v[84:85], s[0:1] op_sel_hi:[1,0]
	v_pk_mul_f32 v[110:111], v[82:83], s[0:1] op_sel_hi:[1,0]
	v_pk_mul_f32 v[108:109], v[80:81], s[0:1] op_sel_hi:[1,0]
	v_pk_mul_f32 v[94:95], v[78:79], s[0:1] op_sel_hi:[1,0]
	v_pk_mul_f32 v[92:93], v[76:77], s[0:1] op_sel_hi:[1,0]
	v_pk_mul_f32 v[98:99], v[70:71], s[0:1] op_sel_hi:[1,0]
	v_pk_mul_f32 v[96:97], v[68:69], s[0:1] op_sel_hi:[1,0]
	v_pk_mul_f32 v[114:115], v[74:75], s[0:1] op_sel_hi:[1,0]
	v_pk_mul_f32 v[112:113], v[72:73], s[0:1] op_sel_hi:[1,0]
	v_pk_mul_f32 v[84:85], v[64:65], s[0:1] op_sel_hi:[1,0]
	v_pk_mul_f32 v[78:79], v[62:63], s[0:1] op_sel_hi:[1,0]
	v_pk_mul_f32 v[76:77], v[60:61], s[0:1] op_sel_hi:[1,0]
	v_pk_mul_f32 v[64:65], v[48:49], s[0:1] op_sel_hi:[1,0]
	v_pk_mul_f32 v[70:71], v[58:59], s[0:1] op_sel_hi:[1,0]
	v_pk_mul_f32 v[68:69], v[56:57], s[0:1] op_sel_hi:[1,0]
	v_pk_mul_f32 v[62:63], v[46:47], s[0:1] op_sel_hi:[1,0]
	v_pk_mul_f32 v[60:61], v[44:45], s[0:1] op_sel_hi:[1,0]
	s_lshl_b32 s1, s39, 13
	s_lshl_b32 s20, s40, 12
	s_waitcnt vmcnt(2)
	s_barrier
	global_load_lds_dwordx4 v[6:7], off
	v_lshl_add_u64 v[6:7], v[100:101], 0, s[18:19]
	s_add_i32 m0, s17, 0x1a000
	s_add_i32 s50, s17, 0x8000
	s_add_i32 s51, s17, 0xa000
	global_load_lds_dwordx4 v[6:7], off
	v_lshl_add_u64 v[6:7], v[90:91], 0, s[18:19]
	s_mov_b32 m0, s50
	s_add_u32 s2, s26, 0x40080
	global_load_lds_dwordx4 v[6:7], off
	v_lshl_add_u64 v[6:7], v[88:89], 0, s[18:19]
	s_mov_b32 m0, s51
	s_addc_u32 s3, s27, 0
	global_load_lds_dwordx4 v[6:7], off
	s_add_i32 m0, s17, 0x1c000
	v_lshl_add_u64 v[6:7], s[2:3], 0, v[168:169]
	global_load_lds_dwordx4 v[6:7], off
	v_lshl_add_u64 v[6:7], s[2:3], 0, v[170:171]
	s_add_i32 m0, s17, 0x1e000
	v_pk_mul_f32 v[48:49], v[4:5], s[0:1] op_sel_hi:[1,0]
	global_load_lds_dwordx4 v[6:7], off
	v_pk_mul_f32 v[122:123], v[2:3], s[0:1] op_sel_hi:[1,0]
	v_pk_mul_f32 v[120:121], v[0:1], s[0:1] op_sel_hi:[1,0]
	v_pk_mul_f32 v[126:127], v[22:23], s[0:1] op_sel_hi:[1,0]
	v_pk_mul_f32 v[124:125], v[20:21], s[0:1] op_sel_hi:[1,0]
	v_pk_mul_f32 v[118:119], v[18:19], s[0:1] op_sel_hi:[1,0]
	v_pk_mul_f32 v[116:117], v[16:17], s[0:1] op_sel_hi:[1,0]
	v_pk_mul_f32 v[102:103], v[14:15], s[0:1] op_sel_hi:[1,0]
	v_pk_mul_f32 v[100:101], v[12:13], s[0:1] op_sel_hi:[1,0]
	v_pk_mul_f32 v[90:91], v[10:11], s[0:1] op_sel_hi:[1,0]
	v_pk_mul_f32 v[88:89], v[8:9], s[0:1] op_sel_hi:[1,0]
	v_pk_mul_f32 v[82:83], v[38:39], s[0:1] op_sel_hi:[1,0]
	v_pk_mul_f32 v[80:81], v[36:37], s[0:1] op_sel_hi:[1,0]
	v_pk_mul_f32 v[74:75], v[34:35], s[0:1] op_sel_hi:[1,0]
	v_pk_mul_f32 v[72:73], v[32:33], s[0:1] op_sel_hi:[1,0]
	v_pk_mul_f32 v[58:59], v[30:31], s[0:1] op_sel_hi:[1,0]
	v_pk_mul_f32 v[56:57], v[28:29], s[0:1] op_sel_hi:[1,0]
	v_pk_mul_f32 v[46:47], v[26:27], s[0:1] op_sel_hi:[1,0]
	v_pk_mul_f32 v[44:45], v[24:25], s[0:1] op_sel_hi:[1,0]
	v_pk_mul_f32 v[54:55], v[54:55], s[0:1] op_sel_hi:[1,0]
	v_pk_mul_f32 v[52:53], v[52:53], s[0:1] op_sel_hi:[1,0]
	v_pk_mul_f32 v[42:43], v[42:43], s[0:1] op_sel_hi:[1,0]
	v_pk_mul_f32 v[40:41], v[40:41], s[0:1] op_sel_hi:[1,0]
	v_pk_mul_f32 v[38:39], v[134:135], s[0:1] op_sel_hi:[1,0]
	v_pk_mul_f32 v[36:37], v[132:133], s[0:1] op_sel_hi:[1,0]
	v_pk_mul_f32 v[30:31], v[130:131], s[0:1] op_sel_hi:[1,0]
	v_pk_mul_f32 v[28:29], v[128:129], s[0:1] op_sel_hi:[1,0]
	v_pk_mul_f32 v[34:35], v[150:151], s[0:1] op_sel_hi:[1,0]
	v_pk_mul_f32 v[32:33], v[148:149], s[0:1] op_sel_hi:[1,0]
	v_pk_mul_f32 v[26:27], v[146:147], s[0:1] op_sel_hi:[1,0]
	v_pk_mul_f32 v[24:25], v[144:145], s[0:1] op_sel_hi:[1,0]
	v_pk_mul_f32 v[22:23], v[142:143], s[0:1] op_sel_hi:[1,0]
	v_pk_mul_f32 v[20:21], v[140:141], s[0:1] op_sel_hi:[1,0]
	v_pk_mul_f32 v[14:15], v[138:139], s[0:1] op_sel_hi:[1,0]
	v_pk_mul_f32 v[12:13], v[136:137], s[0:1] op_sel_hi:[1,0]
	v_pk_mul_f32 v[18:19], v[166:167], s[0:1] op_sel_hi:[1,0]
	v_pk_mul_f32 v[16:17], v[164:165], s[0:1] op_sel_hi:[1,0]
	v_pk_mul_f32 v[10:11], v[162:163], s[0:1] op_sel_hi:[1,0]
	v_pk_mul_f32 v[8:9], v[160:161], s[0:1] op_sel_hi:[1,0]
	v_pk_mul_f32 v[6:7], v[158:159], s[0:1] op_sel_hi:[1,0]
	v_pk_mul_f32 v[4:5], v[156:157], s[0:1] op_sel_hi:[1,0]
	v_pk_mul_f32 v[2:3], v[154:155], s[0:1] op_sel_hi:[1,0]
	v_pk_mul_f32 v[0:1], v[152:153], s[0:1] op_sel_hi:[1,0]
	v_and_b32_e32 v128, 48, v183
	v_lshlrev_b32_e32 v129, 6, v181
	s_movk_i32 s0, 0x3c0
	v_lshlrev_b32_e32 v130, 2, v181
	v_and_or_b32 v129, v129, s0, v128
	v_and_b32_e32 v130, 32, v130
	v_bitop3_b32 v132, v129, s1, v130 bitop3:0xde
	v_lshlrev_b32_e32 v129, 2, v184
	v_lshl_or_b32 v128, v184, 6, v128
	v_and_b32_e32 v129, 32, v129
	v_bitop3_b32 v140, v128, s20, v129 bitop3:0xde
	v_lshlrev_b32_e32 v128, 14, v185
	v_lshlrev_b32_e32 v130, 14, v188
	v_and_b32_e32 v128, 0xffff8000, v128
	v_and_b32_e32 v130, 0xffff8000, v130
	v_lshl_add_u32 v128, v186, 11, v128
	v_and_b32_e32 v129, 1, v185
	v_lshl_add_u32 v130, v189, 11, v130
	v_and_b32_e32 v131, 1, v188
	s_waitcnt vmcnt(6)
	v_lshl_or_b32 v128, v129, 6, v128
	v_lshl_or_b32 v130, v131, 6, v130
	s_mov_b64 s[0:1], 0x40080
	v_lshl_add_u32 v128, v187, 1, v128
	v_mov_b32_e32 v129, v169
	v_lshl_add_u32 v130, v190, 1, v130
	v_mov_b32_e32 v131, v169
	v_lshl_add_u64 v[128:129], v[128:129], 0, s[0:1]
	v_lshl_add_u64 v[130:131], v[130:131], 0, s[0:1]
	s_add_i32 s52, 0, 0x10000
	s_add_i32 s53, 0, 0x14000
	v_add_u32_e32 v141, 0, v132
	v_mov_b64_e32 v[132:133], 0x100
	v_mov_b64_e32 v[134:135], 0xff
	s_barrier
	s_branch .LBB0_3583
